# weight bf16 conversion for layers 1-3 moved from the prologue into the idle tail of the G1 phases (workgroups without a 7th tile)
# speedup vs baseline: 1.0218x; 1.0113x over previous
; #define LAS __attribute__((address_space(3)))
; #define LDS_WAIT() asm volatile("s_waitcnt lgkmcnt(0)" ::: "memory")
; #pragma unroll 8
;     for (int i = 0; i < 32; ++i) { const int kk = 2 * i + (lane >> 5); scr[kk * 33 + (lane & 31)] = __builtin_nontemporal_load(W + (size_t)(k0 + kk) * N + n0 + (lane & 31)); }
;     LDS_WAIT(); asm volatile("" ::: "memory");
;     const int c = lane & 7;
; #pragma unroll
;     for (int j = 0; j < 4; ++j) { const int n = (lane >> 3) + 8 * j; const LAS float* s = scr + (8 * c) * 33 + n;
; __device__ __forceinline__ void prologue_a(const Args& a, LAS unsigned char* lds, int tid, int G) {
;     ...
;         const int gw = blockIdx.x * 8 + wave, NGW = G * 8;
;         constexpr int PER_L = 10240;
;         for (int it = gw; it < DEPTH * PER_L; it += NGW) {
;             const int l = it / PER_L; int r = it % PER_L;
;             if (r < 5632) {
;                 const int up = r >= 2816; if (up) r -= 2816;
;                 const int sub = r / 1408, rr = r % 1408, kb = rr / 88, nb = rr % 88, n0 = nb * 32;
;                 const float* W = a.in[up ? I_WU : I_WG] + (size_t)(l * 2 + sub) * DM * DFF;
;                 bf16_t* WT = (bf16_t*)(ws + WS_WGU) + (size_t)(l * 2 + sub) * NGU * DM;
;                 transpose_item(W, DFF, kb * 64, n0, WT, DM, 256 * (n0 >> 7) + (up ? 128 : 0) + (n0 & 127) - n0, scr, lane, up ? (1.0f / LOG2E) : LOG2E);
.LBB0_26:
	s_and_b64 vcc, exec, s[8:9]
	s_cbranch_vccz .LBB0_600
	s_mov_b32 s100, s99
	s_mov_b32 s101, s98
	s_movk_i32 s32, 0x2800
.Ldef_entry:
	v_ashrrev_i32_e32 v0, 6, v158
	s_waitcnt lgkmcnt(0)
	v_add_u32_e32 v3, s100, v0
	s_mov_b32 s0, 0xa000
	s_waitcnt vmcnt(0)
	v_and_b32_e32 v38, 63, v158
	v_cmp_gt_i32_e32 vcc, s32, v3
	s_and_saveexec_b64 s[0:1], vcc
	s_cbranch_execz .LBB0_52
	v_lshlrev_b32_e32 v2, 3, v38
	v_lshlrev_b32_e32 v0, 14, v0
	v_lshrrev_b32_e32 v39, 3, v38
	v_and_b32_e32 v2, 56, v2
	v_add_u32_e32 v4, 0, v0
	v_lshrrev_b32_e32 v13, 5, v38
	v_mul_u32_u24_e32 v5, 0x84, v2
	v_lshlrev_b32_e32 v6, 2, v39
	v_add3_u32 v40, v4, v5, v6
	v_mul_u32_u24_e32 v4, 0x84, v13
	v_or_b32_e32 v0, v0, v4
	v_lshlrev_b32_e32 v4, 2, v158
	v_and_b32_e32 v4, 0x7c, v4
	v_readlane_b32 s40, v254, 11
	v_bfe_u32 v12, v158, 5, 1
	v_add3_u32 v44, v0, v4, 0
	v_mov_b32_e32 v5, v1
	v_readlane_b32 s44, v254, 15
	v_readlane_b32 s45, v254, 16
	v_readlane_b32 s46, v254, 17
	v_readlane_b32 s47, v254, 18
	v_readlane_b32 s48, v254, 19
	v_readlane_b32 s49, v254, 20
	v_lshl_or_b32 v0, v12, 12, v4
	v_or_b32_e32 v41, 8, v39
	v_or_b32_e32 v42, 16, v39
	v_or_b32_e32 v43, 24, v39
	v_lshl_add_u64 v[6:7], s[48:49], 0, v[4:5]
	v_or_b32_e32 v45, 0xffffb40e, v13
	v_or_b32_e32 v46, 0xffffb40c, v13
	v_or_b32_e32 v47, 0xffffb40a, v13
	v_or_b32_e32 v48, 0xffffb408, v13
	v_or_b32_e32 v49, 0xffffb406, v13
	v_or_b32_e32 v50, 0xffffb404, v13
	v_or_b32_e32 v51, 0xffffb402, v13
	v_or_b32_e32 v52, 0xffffb400, v13
	v_lshl_add_u64 v[8:9], s[46:47], 0, v[4:5]
	v_or_b32_e32 v53, 14, v13
	v_or_b32_e32 v54, 12, v13
	v_or_b32_e32 v55, 10, v13
	v_or_b32_e32 v56, 8, v13
	v_or_b32_e32 v57, 6, v13
	v_or_b32_e32 v58, 4, v13
	v_or_b32_e32 v59, 2, v13
	v_lshl_add_u64 v[10:11], s[44:45], 0, v[4:5]
	v_lshl_add_u64 v[14:15], s[44:45], 0, v[0:1]
	s_mov_b64 s[8:9], 0
	v_readlane_b32 s41, v254, 12
	v_readlane_b32 s42, v254, 13
	v_readlane_b32 s43, v254, 14
	v_readlane_b32 s50, v254, 21
	v_readlane_b32 s51, v254, 22
	v_readlane_b32 s52, v254, 23
	v_readlane_b32 s53, v254, 24
	v_readlane_b32 s54, v254, 25
	v_readlane_b32 s55, v254, 26
	s_branch .LBB0_30
.LBB0_29:
	s_or_b64 exec, exec, s[10:11]
	v_add_u32_e32 v3, s101, v3
	s_add_i32 s3, s32, -1
	v_cmp_lt_i32_e32 vcc, s3, v3
	s_or_b64 s[8:9], vcc, s[8:9]
	s_andn2_b64 exec, exec, s[8:9]
	s_cbranch_execz .LBB0_52

; __device__ __forceinline__ unsigned cvt_pk_bf16(float lo, float hi) { unsigned r; asm volatile("v_cvt_pk_bf16_f32 %0, %1, %2" : "=v"(r) : "v"(lo), "v"(hi)); return r; }
; __device__ __forceinline__ void prologue_a(const Args& a, LAS unsigned char* lds, int tid, int G) {
;     ...
;         const float* wsrc = a.in[I_WS]; bf16_t* wdst = (bf16_t*)(ws + WS_WS);
;         for (int i = (blockIdx.x * 512 + tid); i < DEPTH * 4 * 128 * 128 / 8; i += G * 512) {
;             const f32x4 v0 = *(const f32x4*)(wsrc + (size_t)i * 8), v1 = *(const f32x4*)(wsrc + (size_t)i * 8 + 4);
;             *(u32x4*)(wdst + (size_t)i * 8) = (u32x4){cvt_pk_bf16(v0[0], v0[1]), cvt_pk_bf16(v0[2], v0[3]), cvt_pk_bf16(v1[0], v1[1]), cvt_pk_bf16(v1[2], v1[3])};
;         }
.LBB0_52:
	s_or_b64 exec, exec, s[0:1]
	s_cmp_lg_u32 s6, 0
	s_cbranch_scc1 .Ldef_ret
	v_readlane_b32 s0, v252, 18
	s_nop 1
	v_add_u32_e32 v2, s0, v158
	s_mov_b32 s0, 0x8000
	v_cmp_gt_i32_e32 vcc, s0, v2
	s_and_saveexec_b64 s[0:1], vcc
	s_cbranch_execz .LBB0_55
	v_ashrrev_i32_e32 v3, 31, v2
	v_readlane_b32 s8, v254, 27
	v_lshlrev_b64 v[4:5], 5, v[2:3]
	v_readlane_b32 s9, v254, 28
	s_nop 1
	v_lshl_add_u64 v[4:5], s[8:9], 0, v[4:5]
	v_readlane_b32 s8, v252, 16
	v_readlane_b32 s9, v252, 17
	s_nop 1
	v_lshl_add_u64 v[6:7], v[2:3], 4, s[8:9]
	s_mov_b64 s[8:9], 0

; #define PG8_WAIT_V(n) asm volatile("s_waitcnt vmcnt(" #n ")" ::: "memory")
; #define PG8_BAR __builtin_amdgcn_s_barrier()
; template <class Epi, class Sched, bool ALIGN_EPI = false, bool SP2 = false>
; __device__ __forceinline__ void gemm_phase(LAS unsigned char* lds, const Gemm g, const Sched& S, const Epi& E, const int tid) {
;     ...
;     PG8_WAIT_V(0);
;     if constexpr (!ALIGN_EPI) { if (wr == 0) PG8_BAR; }
;     PG8_BAR;
; __global__ void __launch_bounds__(512, 2) mega_fwd(Args a) {
;     ...
;             const int q = p - 2, l = q / 10, st = q % 10; const bool last = (l == DEPTH - 1);
;             const int Mfull = TT, Mlate = last ? T_LAT : TT;
;             if (st == 0 || st == 7) {
;                 const int sub = (st == 7), M = sub ? Mlate : Mfull;
;                 pg8::Gemm g{(const bf16_t*)(ws + WS_Y), (const bf16_t*)(ws + WS_WGU) + (size_t)(l * 2 + sub) * NGU * DM, M, NGU, DM};
;                 pg8::StaticOrder S; S.init(M, NGU, G, (int)blockIdx.x); S.nkt = DM / pg8::BK;
;                 pg8::EpiSwiGLU E{(bf16_t*)(ws + WS_R1)};
;                 pg8::gemm_phase<pg8::EpiSwiGLU, pg8::StaticOrder, true, true>(lds, g, S, E, tid);
.LBB0_598:
	s_waitcnt vmcnt(0)
	v_readlane_b32 s22, v254, 35
	v_readlane_b32 s24, v254, 37
	v_readlane_b32 s0, v254, 39
	v_readlane_b32 s60, v254, 41
	v_readlane_b32 s28, v254, 43
	v_readlane_b32 s20, v254, 45
	s_barrier
	v_readlane_b32 s23, v254, 36
	v_readlane_b32 s25, v254, 38
	v_readlane_b32 s1, v254, 40
	s_mov_b32 s26, s0
	v_readlane_b32 s61, v254, 42
	v_readlane_b32 s29, v254, 44
	v_readlane_b32 s21, v254, 46
	s_add_i32 s8, s6, -2
	s_mul_hi_u32 s9, s8, 0xcccccccd
	s_lshr_b32 s9, s9, 3
	s_mul_i32 s10, s9, 10
	s_sub_i32 s10, s8, s10
	s_cmp_gt_u32 s9, 2
	s_cbranch_scc1 .Ldef_skip
	s_cmp_lt_u32 s2, 48
	s_cbranch_scc1 .Ldef_skip
	s_add_i32 s9, s9, 1
	s_mul_i32 s9, s9, 0x2800
	s_cmp_eq_u32 s10, 7
	s_cselect_b32 s10, 0x1400, 0
	s_add_i32 s9, s9, s10
	s_add_i32 s32, s9, 0x1400
	s_add_i32 s100, s9, s99
	s_add_i32 s100, s100, 0xfffffe80
	s_movk_i32 s101, 0x680
	s_branch .Ldef_entry
.Ldef_ret:
	v_readlane_b32 s0, v254, 39
	v_readlane_b32 s20, v254, 45
	v_readlane_b32 s1, v254, 40
	v_readlane_b32 s21, v254, 46
.Ldef_skip:
.LBB0_599:
	s_mov_b32 s16, 0x800000

; __global__ void __launch_bounds__(512, 2) mega_fwd(Args a) {
	.amdhsa_kernel _Z8mega_fwd4Args
		.amdhsa_group_segment_fixed_size 0
		.amdhsa_private_segment_fixed_size 0
		.amdhsa_kernarg_size 432
		.amdhsa_user_sgpr_count 2
		.amdhsa_user_sgpr_dispatch_ptr 0
		.amdhsa_user_sgpr_queue_ptr 0
		.amdhsa_user_sgpr_kernarg_segment_ptr 1
		.amdhsa_user_sgpr_dispatch_id 0
		.amdhsa_user_sgpr_kernarg_preload_length 0
		.amdhsa_user_sgpr_kernarg_preload_offset 0
		.amdhsa_user_sgpr_private_segment_size 0
		.amdhsa_uses_dynamic_stack 0
		.amdhsa_enable_private_segment 0
		.amdhsa_system_sgpr_workgroup_id_x 1
		.amdhsa_system_sgpr_workgroup_id_y 0
		.amdhsa_system_sgpr_workgroup_id_z 0
		.amdhsa_system_sgpr_workgroup_info 0
		.amdhsa_system_vgpr_workitem_id 2
		.amdhsa_next_free_vgpr 256
		.amdhsa_next_free_sgpr 102
		.amdhsa_accum_offset 256
		.amdhsa_reserve_vcc 1
		.amdhsa_float_round_mode_32 0
		.amdhsa_float_round_mode_16_64 0
		.amdhsa_float_denorm_mode_32 3
		.amdhsa_float_denorm_mode_16_64 3
		.amdhsa_dx10_clamp 1
		.amdhsa_ieee_mode 1
		.amdhsa_fp16_overflow 0
		.amdhsa_tg_split 0
		.amdhsa_exception_fp_ieee_invalid_op 0
		.amdhsa_exception_fp_denorm_src 0
		.amdhsa_exception_fp_ieee_div_zero 0
		.amdhsa_exception_fp_ieee_overflow 0
		.amdhsa_exception_fp_ieee_underflow 0
		.amdhsa_exception_fp_ieee_inexact 0
		.amdhsa_exception_int_div_zero 0
	.end_amdhsa_kernel

; __global__ void __launch_bounds__(512, 2) mega_fwd(Args a) {
amdhsa.kernels:
  - .agpr_count:     0
    .args:
      - .offset:         0
        .size:           176
        .value_kind:     by_value
      - .offset:         176
        .size:           4
        .value_kind:     hidden_block_count_x
      - .offset:         180
        .size:           4
        .value_kind:     hidden_block_count_y
      - .offset:         184
        .size:           4
        .value_kind:     hidden_block_count_z
      - .offset:         188
        .size:           2
        .value_kind:     hidden_group_size_x
      - .offset:         190
        .size:           2
        .value_kind:     hidden_group_size_y
      - .offset:         192
        .size:           2
        .value_kind:     hidden_group_size_z
      - .offset:         194
        .size:           2
        .value_kind:     hidden_remainder_x
      - .offset:         196
        .size:           2
        .value_kind:     hidden_remainder_y
      - .offset:         198
        .size:           2
        .value_kind:     hidden_remainder_z
      - .offset:         216
        .size:           8
        .value_kind:     hidden_global_offset_x
      - .offset:         224
        .size:           8
        .value_kind:     hidden_global_offset_y
      - .offset:         232
        .size:           8
        .value_kind:     hidden_global_offset_z
      - .offset:         240
        .size:           2
        .value_kind:     hidden_grid_dims
      - .offset:         264
        .size:           8
        .value_kind:     hidden_multigrid_sync_arg
      - .offset:         296
        .size:           4
        .value_kind:     hidden_dynamic_lds_size
    .group_segment_fixed_size: 0
    .kernarg_segment_align: 8
    .kernarg_segment_size: 432
    .language:       OpenCL C
    .language_version:
      - 2
      - 0
    .max_flat_workgroup_size: 512
    .name:           _Z8mega_fwd4Args
    .private_segment_fixed_size: 0
    .sgpr_count:     108
    .sgpr_spill_count: 246
    .symbol:         _Z8mega_fwd4Args.kd
    .uniform_work_group_size: 1
    .uses_dynamic_stack: false
    .vgpr_count:     256
    .vgpr_spill_count: 0
    .wavefront_size: 64
